# v022 with an MFMA-first QK^T head: the finishSM VALU that sat between the barrier and the first QK^T MFMA is merged into the MFMA gaps (light first gaps, exps spread)
# speedup vs baseline: 1.0011x; 1.0011x over previous
.Lprio_skip:
	s_sub_i32 s10, s54, 63
	s_cmp_le_i32 s10, s5
	s_cselect_b64 s[76:77], -1, 0
	s_cmp_gt_i32 s10, s5
	s_cbranch_scc1 .LBB0_396
	ds_read_b128 v[236:239], v196 offset:57344
	ds_read_b128 v[240:243], v207 offset:12288
	ds_read_b128 v[246:249], v197 offset:57344
	ds_read_b128 v[250:253], v205 offset:12288
	ds_read_b128 v[6:9], v195
	ds_read_b128 v[10:13], v195 offset:1024
	ds_read_b128 v[2:5], v195 offset:2048
	s_waitcnt lgkmcnt(6)
	v_mfma_f32_32x32x16_bf16 v[112:127], v[236:239], v[156:159], 0
	ds_read_b128 v[236:239], v199 offset:57344
	v_cvt_pk_bf16_f32 v18, v224, v226
	v_add_f32_e32 v0, 0, v224
	s_waitcnt lgkmcnt(6)
	v_mfma_f32_32x32x16_bf16 v[96:111], v[240:243], v[156:159], 0
	ds_read_b128 v[240:243], v206 offset:12288
	v_cvt_pk_bf16_f32 v19, v222, v225
	v_add_f32_e32 v0, v226, v0
	s_waitcnt lgkmcnt(6)
	v_mfma_f32_32x32x16_bf16 v[112:127], v[246:249], v[152:155], v[112:127]
	ds_read_b128 v[246:249], v198 offset:57344
	v_cvt_pk_bf16_f32 v20, v220, v223
	v_add_f32_e32 v0, v222, v0
	v_cvt_pk_bf16_f32 v21, v219, v221
	s_waitcnt lgkmcnt(6)
	v_mfma_f32_32x32x16_bf16 v[96:111], v[250:253], v[152:155], v[96:111]
	ds_read_b128 v[250:253], v204 offset:12288
	v_add_f32_e32 v0, v225, v0
	v_cvt_pk_bf16_f32 v22, v216, v218
	v_add_f32_e32 v0, v220, v0
	s_waitcnt lgkmcnt(3)
	v_mfma_f32_32x32x16_bf16 v[112:127], v[236:239], v[148:151], v[112:127]
	ds_read_b128 v[236:239], v196 offset:57472
	v_cvt_pk_bf16_f32 v23, v214, v217
	v_add_f32_e32 v0, v223, v0
	v_cvt_pk_bf16_f32 v24, v212, v215
	s_waitcnt lgkmcnt(3)
	v_mfma_f32_32x32x16_bf16 v[96:111], v[240:243], v[148:151], v[96:111]
	ds_read_b128 v[240:243], v207 offset:12416
	v_add_f32_e32 v0, v219, v0
	v_cvt_pk_bf16_f32 v25, v211, v213
	v_add_f32_e32 v0, v221, v0
	s_waitcnt lgkmcnt(3)
	v_mfma_f32_32x32x16_bf16 v[112:127], v[246:249], v[144:147], v[112:127]
	ds_read_b128 v[246:249], v197 offset:57472
	v_add_f32_e32 v0, v216, v0
	v_add_f32_e32 v0, v218, v0
	v_permlane32_swap_b32_e32 v18, v20
	s_waitcnt lgkmcnt(3)
	v_mfma_f32_32x32x16_bf16 v[96:111], v[250:253], v[144:147], v[96:111]
	ds_read_b128 v[250:253], v205 offset:12416
	v_add_f32_e32 v0, v214, v0
	v_add_f32_e32 v0, v217, v0
	v_permlane32_swap_b32_e32 v19, v21
	s_waitcnt lgkmcnt(3)
	v_mfma_f32_32x32x16_bf16 v[112:127], v[236:239], v[140:143], v[112:127]
	ds_read_b128 v[236:239], v199 offset:57472
	v_add_f32_e32 v0, v212, v0
	v_add_f32_e32 v0, v215, v0
	v_permlane32_swap_b32_e32 v22, v24
	s_waitcnt lgkmcnt(3)
	v_mfma_f32_32x32x16_bf16 v[96:111], v[240:243], v[140:143], v[96:111]
	ds_read_b128 v[240:243], v206 offset:12416
	v_add_f32_e32 v0, v211, v0
	v_add_f32_e32 v0, v213, v0
	v_permlane32_swap_b32_e32 v23, v25
	s_waitcnt lgkmcnt(3)
	v_mfma_f32_32x32x16_bf16 v[112:127], v[246:249], v[136:139], v[112:127]
	ds_read_b128 v[246:249], v198 offset:57472
	v_exp_f32_e32 v182, v182
	v_exp_f32_e32 v183, v183
	v_exp_f32_e32 v180, v180
	s_waitcnt lgkmcnt(3)
	v_mfma_f32_32x32x16_bf16 v[96:111], v[250:253], v[136:139], v[96:111]
	ds_read_b128 v[250:253], v204 offset:12416
	v_exp_f32_e32 v181, v181
	v_add_f32_e32 v0, v182, v0
	v_exp_f32_e32 v170, v170
	s_waitcnt lgkmcnt(3)
	v_mfma_f32_32x32x16_bf16 v[112:127], v[236:239], v[132:135], v[112:127]
	ds_read_b128 v[236:239], v196 offset:57600
	v_add_f32_e32 v0, v183, v0
	v_exp_f32_e32 v171, v171
	v_add_f32_e32 v0, v180, v0
	s_waitcnt lgkmcnt(3)
	v_mfma_f32_32x32x16_bf16 v[96:111], v[240:243], v[132:135], v[96:111]
	ds_read_b128 v[240:243], v207 offset:12544
	v_exp_f32_e32 v168, v168
	v_add_f32_e32 v0, v181, v0
	v_exp_f32_e32 v169, v169
	s_waitcnt lgkmcnt(3)
	v_mfma_f32_32x32x16_bf16 v[112:127], v[246:249], v[128:131], v[112:127]
	ds_read_b128 v[246:249], v197 offset:57600
	v_cvt_pk_bf16_f32 v26, v182, v183
	v_cvt_pk_bf16_f32 v27, v180, v181
	v_add_f32_e32 v0, v170, v0
	s_waitcnt lgkmcnt(3)
	v_mfma_f32_32x32x16_bf16 v[96:111], v[250:253], v[128:131], v[96:111]
	ds_read_b128 v[250:253], v205 offset:12544
	v_exp_f32_e32 v166, v166
	v_add_f32_e32 v0, v171, v0
	v_exp_f32_e32 v167, v167
	s_waitcnt lgkmcnt(3)
	v_mfma_f32_32x32x16_bf16 v[112:127], v[236:239], v[6:9], v[112:127]
	ds_read_b128 v[236:239], v199 offset:57600
	v_add_f32_e32 v0, v168, v0
	v_exp_f32_e32 v164, v164
	v_add_f32_e32 v0, v169, v0
	s_waitcnt lgkmcnt(3)
	v_mfma_f32_32x32x16_bf16 v[96:111], v[240:243], v[6:9], v[96:111]
	ds_read_b128 v[240:243], v206 offset:12544
	ds_read_b128 v[6:9], v195 offset:3072
	v_exp_f32_e32 v165, v165
	v_cvt_pk_bf16_f32 v28, v170, v171
	v_cvt_pk_bf16_f32 v29, v168, v169
	s_waitcnt lgkmcnt(4)
	v_mfma_f32_32x32x16_bf16 v[112:127], v[246:249], v[10:13], v[112:127]
	ds_read_b128 v[246:249], v198 offset:57600
	v_add_f32_e32 v0, v166, v0
	v_exp_f32_e32 v162, v162
	v_permlane32_swap_b32_e32 v26, v28
	s_waitcnt lgkmcnt(4)
	v_mfma_f32_32x32x16_bf16 v[96:111], v[250:253], v[10:13], v[96:111]
	ds_read_b128 v[250:253], v204 offset:12544
	v_permlane32_swap_b32_e32 v27, v29
	v_add_f32_e32 v0, v167, v0
	v_exp_f32_e32 v163, v163
	s_waitcnt lgkmcnt(4)
	v_mfma_f32_32x32x16_bf16 v[112:127], v[236:239], v[2:5], v[112:127]
	v_add_f32_e32 v0, v164, v0
	v_exp_f32_e32 v160, v160
	s_waitcnt lgkmcnt(3)
	v_mfma_f32_32x32x16_bf16 v[96:111], v[240:243], v[2:5], v[96:111]
	v_add_f32_e32 v0, v165, v0
	v_exp_f32_e32 v161, v161
	s_waitcnt lgkmcnt(1)
	v_mfma_f32_32x32x16_bf16 v[112:127], v[246:249], v[6:9], v[112:127]
	v_cvt_pk_bf16_f32 v168, v166, v167
	v_cvt_pk_bf16_f32 v169, v164, v165
	s_waitcnt lgkmcnt(0)
	v_mfma_f32_32x32x16_bf16 v[96:111], v[250:253], v[6:9], v[96:111]
	v_add_f32_e32 v0, v162, v0
	v_add_f32_e32 v0, v163, v0
	v_add_f32_e32 v0, v160, v0
	v_add_f32_e32 v0, v161, v0
	v_cvt_pk_bf16_f32 v170, v162, v163
	v_cvt_pk_bf16_f32 v171, v160, v161
	v_mov_b32_e32 v14, v0
	s_nop 1
	v_permlane32_swap_b32_e32 v168, v170
	v_permlane32_swap_b32_e32 v169, v171
	v_permlane32_swap_b32_e32 v0, v14
	s_branch .Lattn_h1_join

.Lqh1_norsc:
	v_fmamk_f32 v168, v102, 0x3dd53b94, v254
	v_fmamk_f32 v169, v103, 0x3dd53b94, v254
	v_fmamk_f32 v170, v100, 0x3dd53b94, v254
	v_fmamk_f32 v171, v101, 0x3dd53b94, v254
	s_waitcnt lgkmcnt(6)
	v_mfma_f32_32x32x16_bf16 v[112:127], v[236:239], v[156:159], 0
	ds_read_b128 v[236:239], v199 offset:57344
	v_cvt_pk_bf16_f32 v18, v224, v226
	v_add_f32_e32 v0, 0, v224
	s_waitcnt lgkmcnt(6)
	v_mfma_f32_32x32x16_bf16 v[96:111], v[240:243], v[156:159], 0
	ds_read_b128 v[240:243], v206 offset:12288
	v_cvt_pk_bf16_f32 v19, v222, v225
	v_add_f32_e32 v0, v226, v0
	s_waitcnt lgkmcnt(6)
	v_mfma_f32_32x32x16_bf16 v[112:127], v[246:249], v[152:155], v[112:127]
	ds_read_b128 v[246:249], v198 offset:57344
	v_cvt_pk_bf16_f32 v20, v220, v223
	v_add_f32_e32 v0, v222, v0
	v_cvt_pk_bf16_f32 v21, v219, v221
	s_waitcnt lgkmcnt(6)
	v_mfma_f32_32x32x16_bf16 v[96:111], v[250:253], v[152:155], v[96:111]
	ds_read_b128 v[250:253], v204 offset:12288
	v_add_f32_e32 v0, v225, v0
	v_cvt_pk_bf16_f32 v22, v216, v218
	v_add_f32_e32 v0, v220, v0
	s_waitcnt lgkmcnt(3)
	v_mfma_f32_32x32x16_bf16 v[112:127], v[236:239], v[148:151], v[112:127]
	ds_read_b128 v[236:239], v196 offset:57472
	v_cvt_pk_bf16_f32 v23, v214, v217
	v_add_f32_e32 v0, v223, v0
	v_cvt_pk_bf16_f32 v24, v212, v215
	s_waitcnt lgkmcnt(3)
	v_mfma_f32_32x32x16_bf16 v[96:111], v[240:243], v[148:151], v[96:111]
	ds_read_b128 v[240:243], v207 offset:12416
	v_add_f32_e32 v0, v219, v0
	v_cvt_pk_bf16_f32 v25, v211, v213
	v_add_f32_e32 v0, v221, v0
	s_waitcnt lgkmcnt(3)
	v_mfma_f32_32x32x16_bf16 v[112:127], v[246:249], v[144:147], v[112:127]
	ds_read_b128 v[246:249], v197 offset:57472
	v_add_f32_e32 v0, v216, v0
	v_add_f32_e32 v0, v218, v0
	v_permlane32_swap_b32_e32 v18, v20
	s_waitcnt lgkmcnt(3)
	v_mfma_f32_32x32x16_bf16 v[96:111], v[250:253], v[144:147], v[96:111]
	ds_read_b128 v[250:253], v205 offset:12416
	v_add_f32_e32 v0, v214, v0
	v_add_f32_e32 v0, v217, v0
	v_permlane32_swap_b32_e32 v19, v21
	s_waitcnt lgkmcnt(3)
	v_mfma_f32_32x32x16_bf16 v[112:127], v[236:239], v[140:143], v[112:127]
	ds_read_b128 v[236:239], v199 offset:57472
	v_add_f32_e32 v0, v212, v0
	v_add_f32_e32 v0, v215, v0
	v_permlane32_swap_b32_e32 v22, v24
	s_waitcnt lgkmcnt(3)
	v_mfma_f32_32x32x16_bf16 v[96:111], v[240:243], v[140:143], v[96:111]
	ds_read_b128 v[240:243], v206 offset:12416
	v_add_f32_e32 v0, v211, v0
	v_add_f32_e32 v0, v213, v0
	v_permlane32_swap_b32_e32 v23, v25
	s_waitcnt lgkmcnt(3)
	v_mfma_f32_32x32x16_bf16 v[112:127], v[246:249], v[136:139], v[112:127]
	ds_read_b128 v[246:249], v198 offset:57472
	v_exp_f32_e32 v182, v182
	v_exp_f32_e32 v183, v183
	v_exp_f32_e32 v180, v180
	s_waitcnt lgkmcnt(3)
	v_mfma_f32_32x32x16_bf16 v[96:111], v[250:253], v[136:139], v[96:111]
	ds_read_b128 v[250:253], v204 offset:12416
	v_exp_f32_e32 v181, v181
	v_add_f32_e32 v0, v182, v0
	v_exp_f32_e32 v170, v170
	s_waitcnt lgkmcnt(3)
	v_mfma_f32_32x32x16_bf16 v[112:127], v[236:239], v[132:135], v[112:127]
	ds_read_b128 v[236:239], v196 offset:57600
	v_add_f32_e32 v0, v183, v0
	v_exp_f32_e32 v171, v171
	v_add_f32_e32 v0, v180, v0
	s_waitcnt lgkmcnt(3)
	v_mfma_f32_32x32x16_bf16 v[96:111], v[240:243], v[132:135], v[96:111]
	ds_read_b128 v[240:243], v207 offset:12544
	v_exp_f32_e32 v168, v168
	v_add_f32_e32 v0, v181, v0
	v_exp_f32_e32 v169, v169
	s_waitcnt lgkmcnt(3)
	v_mfma_f32_32x32x16_bf16 v[112:127], v[246:249], v[128:131], v[112:127]
	ds_read_b128 v[246:249], v197 offset:57600
	v_cvt_pk_bf16_f32 v26, v182, v183
	v_cvt_pk_bf16_f32 v27, v180, v181
	v_add_f32_e32 v0, v170, v0
	s_waitcnt lgkmcnt(3)
	v_mfma_f32_32x32x16_bf16 v[96:111], v[250:253], v[128:131], v[96:111]
	ds_read_b128 v[250:253], v205 offset:12544
	v_exp_f32_e32 v166, v166
	v_add_f32_e32 v0, v171, v0
	v_exp_f32_e32 v167, v167
	s_waitcnt lgkmcnt(3)
	v_mfma_f32_32x32x16_bf16 v[112:127], v[236:239], v[6:9], v[112:127]
	ds_read_b128 v[236:239], v199 offset:57600
	v_add_f32_e32 v0, v168, v0
	v_exp_f32_e32 v164, v164
	v_add_f32_e32 v0, v169, v0
	s_waitcnt lgkmcnt(3)
	v_mfma_f32_32x32x16_bf16 v[96:111], v[240:243], v[6:9], v[96:111]
	ds_read_b128 v[240:243], v206 offset:12544
	ds_read_b128 v[6:9], v195 offset:3072
	v_exp_f32_e32 v165, v165
	v_cvt_pk_bf16_f32 v28, v170, v171
	v_cvt_pk_bf16_f32 v29, v168, v169
	s_waitcnt lgkmcnt(4)
	v_mfma_f32_32x32x16_bf16 v[112:127], v[246:249], v[10:13], v[112:127]
	ds_read_b128 v[246:249], v198 offset:57600
	v_add_f32_e32 v0, v166, v0
	v_exp_f32_e32 v162, v162
	v_permlane32_swap_b32_e32 v26, v28
	s_waitcnt lgkmcnt(4)
	v_mfma_f32_32x32x16_bf16 v[96:111], v[250:253], v[10:13], v[96:111]
	ds_read_b128 v[250:253], v204 offset:12544
	v_permlane32_swap_b32_e32 v27, v29
	v_add_f32_e32 v0, v167, v0
	v_exp_f32_e32 v163, v163
	s_waitcnt lgkmcnt(4)
	v_mfma_f32_32x32x16_bf16 v[112:127], v[236:239], v[2:5], v[112:127]
	v_add_f32_e32 v0, v164, v0
	v_exp_f32_e32 v160, v160
	s_waitcnt lgkmcnt(3)
	v_mfma_f32_32x32x16_bf16 v[96:111], v[240:243], v[2:5], v[96:111]
	v_add_f32_e32 v0, v165, v0
	v_exp_f32_e32 v161, v161
	s_waitcnt lgkmcnt(1)
	v_mfma_f32_32x32x16_bf16 v[112:127], v[246:249], v[6:9], v[112:127]
	v_cvt_pk_bf16_f32 v168, v166, v167
	v_cvt_pk_bf16_f32 v169, v164, v165
	s_waitcnt lgkmcnt(0)
	v_mfma_f32_32x32x16_bf16 v[96:111], v[250:253], v[6:9], v[96:111]
	v_add_f32_e32 v0, v162, v0
	v_add_f32_e32 v0, v163, v0
	v_add_f32_e32 v0, v160, v0
	v_add_f32_e32 v0, v161, v0
	v_cvt_pk_bf16_f32 v170, v162, v163
	v_cvt_pk_bf16_f32 v171, v160, v161
	v_mov_b32_e32 v14, v0
	s_nop 1
	v_permlane32_swap_b32_e32 v168, v170
	v_permlane32_swap_b32_e32 v169, v171
	v_permlane32_swap_b32_e32 v0, v14
	s_branch .Lattn_h1_join

.Lqh2_norsc:
	v_fmamk_f32 v171, v122, 0x3dd53b94, v219
	v_fmamk_f32 v169, v124, 0x3dd53b94, v219
	v_fmamk_f32 v168, v126, 0x3dd53b94, v219
	v_fmamk_f32 v170, v127, 0x3dd53b94, v219
	v_fmac_f32_e32 v219, 0x3dd53b94, v111
	s_waitcnt lgkmcnt(6)
	v_mfma_f32_32x32x16_bf16 v[112:127], v[236:239], v[156:159], 0
	ds_read_b128 v[236:239], v199 offset:32768
	v_cvt_pk_bf16_f32 v18, v216, v218
	v_add_f32_e32 v17, 0, v216
	s_waitcnt lgkmcnt(6)
	v_mfma_f32_32x32x16_bf16 v[96:111], v[240:243], v[156:159], 0
	ds_read_b128 v[240:243], v199 offset:45056
	v_exp_f32_e32 v182, v182
	v_cvt_pk_bf16_f32 v19, v214, v217
	s_waitcnt lgkmcnt(6)
	v_mfma_f32_32x32x16_bf16 v[112:127], v[246:249], v[152:155], v[112:127]
	ds_read_b128 v[246:249], v198 offset:32768
	v_add_f32_e32 v17, v218, v17
	v_exp_f32_e32 v208, v208
	v_cvt_pk_bf16_f32 v20, v212, v215
	s_waitcnt lgkmcnt(6)
	v_mfma_f32_32x32x16_bf16 v[96:111], v[250:253], v[152:155], v[96:111]
	ds_read_b128 v[250:253], v198 offset:45056
	v_add_f32_e32 v17, v214, v17
	v_exp_f32_e32 v171, v171
	v_cvt_pk_bf16_f32 v21, v211, v213
	s_waitcnt lgkmcnt(3)
	v_mfma_f32_32x32x16_bf16 v[112:127], v[236:239], v[148:151], v[112:127]
	ds_read_b128 v[236:239], v196 offset:32896
	v_add_f32_e32 v17, v217, v17
	v_exp_f32_e32 v183, v183
	v_add_f32_e32 v17, v212, v17
	v_exp_f32_e32 v169, v169
	s_waitcnt lgkmcnt(3)
	v_mfma_f32_32x32x16_bf16 v[96:111], v[240:243], v[148:151], v[96:111]
	ds_read_b128 v[240:243], v196 offset:45184
	v_cvt_pk_bf16_f32 v22, v182, v208
	v_add_f32_e32 v17, v215, v17
	v_exp_f32_e32 v181, v181
	v_cvt_pk_bf16_f32 v23, v171, v183
	s_waitcnt lgkmcnt(3)
	v_mfma_f32_32x32x16_bf16 v[112:127], v[246:249], v[144:147], v[112:127]
	ds_read_b128 v[246:249], v197 offset:32896
	v_add_f32_e32 v17, v211, v17
	v_exp_f32_e32 v168, v168
	v_add_f32_e32 v17, v213, v17
	v_exp_f32_e32 v170, v170
	s_waitcnt lgkmcnt(3)
	v_mfma_f32_32x32x16_bf16 v[96:111], v[250:253], v[144:147], v[96:111]
	ds_read_b128 v[250:253], v197 offset:45184
	v_cvt_pk_bf16_f32 v24, v169, v181
	v_cvt_pk_bf16_f32 v25, v168, v170
	v_add_f32_e32 v17, v182, v17
	v_add_f32_e32 v17, v208, v17
	s_waitcnt lgkmcnt(3)
	v_mfma_f32_32x32x16_bf16 v[112:127], v[236:239], v[140:143], v[112:127]
	ds_read_b128 v[236:239], v199 offset:32896
	v_permlane32_swap_b32_e32 v18, v20
	v_add_f32_e32 v17, v171, v17
	v_add_f32_e32 v17, v183, v17
	v_permlane32_swap_b32_e32 v19, v21
	s_waitcnt lgkmcnt(3)
	v_mfma_f32_32x32x16_bf16 v[96:111], v[240:243], v[140:143], v[96:111]
	ds_read_b128 v[240:243], v199 offset:45184
	v_add_f32_e32 v17, v169, v17
	v_add_f32_e32 v17, v181, v17
	v_permlane32_swap_b32_e32 v22, v24
	s_waitcnt lgkmcnt(3)
	v_mfma_f32_32x32x16_bf16 v[112:127], v[246:249], v[136:139], v[112:127]
	ds_read_b128 v[246:249], v198 offset:32896
	v_add_f32_e32 v17, v168, v17
	v_add_f32_e32 v17, v170, v17
	v_permlane32_swap_b32_e32 v23, v25
	s_waitcnt lgkmcnt(3)
	v_mfma_f32_32x32x16_bf16 v[96:111], v[250:253], v[136:139], v[96:111]
	ds_read_b128 v[250:253], v198 offset:45184
	v_exp_f32_e32 v220, v220
	v_exp_f32_e32 v221, v221
	v_exp_f32_e32 v222, v222
	s_waitcnt lgkmcnt(3)
	v_mfma_f32_32x32x16_bf16 v[112:127], v[236:239], v[132:135], v[112:127]
	ds_read_b128 v[236:239], v196 offset:33024
	v_exp_f32_e32 v223, v223
	v_add_f32_e32 v17, v220, v17
	v_exp_f32_e32 v224, v224
	s_waitcnt lgkmcnt(3)
	v_mfma_f32_32x32x16_bf16 v[96:111], v[240:243], v[132:135], v[96:111]
	ds_read_b128 v[240:243], v196 offset:45312
	v_add_f32_e32 v17, v221, v17
	v_exp_f32_e32 v225, v225
	v_add_f32_e32 v17, v222, v17
	s_waitcnt lgkmcnt(3)
	v_mfma_f32_32x32x16_bf16 v[112:127], v[246:249], v[128:131], v[112:127]
	ds_read_b128 v[246:249], v197 offset:33024
	v_exp_f32_e32 v226, v226
	v_add_f32_e32 v17, v223, v17
	v_exp_f32_e32 v227, v227
	s_waitcnt lgkmcnt(3)
	v_mfma_f32_32x32x16_bf16 v[96:111], v[250:253], v[128:131], v[96:111]
	ds_read_b128 v[250:253], v197 offset:45312
	v_cvt_pk_bf16_f32 v26, v220, v221
	v_cvt_pk_bf16_f32 v27, v222, v223
	v_add_f32_e32 v17, v224, v17
	s_waitcnt lgkmcnt(3)
	v_mfma_f32_32x32x16_bf16 v[112:127], v[236:239], v[6:9], v[112:127]
	ds_read_b128 v[236:239], v199 offset:33024
	v_exp_f32_e32 v228, v228
	v_add_f32_e32 v17, v225, v17
	v_exp_f32_e32 v229, v229
	s_waitcnt lgkmcnt(3)
	v_mfma_f32_32x32x16_bf16 v[96:111], v[240:243], v[6:9], v[96:111]
	ds_read_b128 v[240:243], v199 offset:45312
	ds_read_b128 v[6:9], v195 offset:3072
	v_add_f32_e32 v17, v226, v17
	v_exp_f32_e32 v230, v230
	v_add_f32_e32 v17, v227, v17
	s_waitcnt lgkmcnt(4)
	v_mfma_f32_32x32x16_bf16 v[112:127], v[246:249], v[10:13], v[112:127]
	ds_read_b128 v[246:249], v198 offset:33024
	v_exp_f32_e32 v231, v231
	v_cvt_pk_bf16_f32 v28, v224, v225
	v_cvt_pk_bf16_f32 v29, v226, v227
	s_waitcnt lgkmcnt(4)
	v_mfma_f32_32x32x16_bf16 v[96:111], v[250:253], v[10:13], v[96:111]
	ds_read_b128 v[250:253], v198 offset:45312
	v_add_f32_e32 v17, v228, v17
	v_exp_f32_e32 v232, v232
	v_permlane32_swap_b32_e32 v26, v28
	s_waitcnt lgkmcnt(4)
	v_mfma_f32_32x32x16_bf16 v[112:127], v[236:239], v[2:5], v[112:127]
	v_permlane32_swap_b32_e32 v27, v29
	v_add_f32_e32 v17, v229, v17
	v_exp_f32_e32 v233, v233
	s_waitcnt lgkmcnt(3)
	v_mfma_f32_32x32x16_bf16 v[96:111], v[240:243], v[2:5], v[96:111]
	v_add_f32_e32 v17, v230, v17
	v_exp_f32_e32 v234, v234
	v_add_f32_e32 v17, v231, v17
	s_waitcnt lgkmcnt(1)
	v_mfma_f32_32x32x16_bf16 v[112:127], v[246:249], v[6:9], v[112:127]
	v_exp_f32_e32 v219, v219
	v_cvt_pk_bf16_f32 v168, v228, v229
	v_cvt_pk_bf16_f32 v169, v230, v231
	s_waitcnt lgkmcnt(0)
	v_mfma_f32_32x32x16_bf16 v[96:111], v[250:253], v[6:9], v[96:111]
	v_add_f32_e32 v17, v232, v17
	v_add_f32_e32 v17, v233, v17
	v_add_f32_e32 v17, v234, v17
	v_add_f32_e32 v17, v219, v17
	v_cvt_pk_bf16_f32 v170, v232, v233
	v_cvt_pk_bf16_f32 v171, v234, v219
	v_mov_b32_e32 v30, v17
	s_nop 1
	v_permlane32_swap_b32_e32 v168, v170
	v_permlane32_swap_b32_e32 v169, v171
	v_permlane32_swap_b32_e32 v17, v30
	s_branch .Lattn_h2_join
